# S5 scan tile loop: next tile's ssq/hs loads are a real prefetch now (wait + ssq reduction moved from the loop latch to the end of the following tile body; body opens with vmcnt(6) instead of vmcnt(0))
# speedup vs baseline: 1.0114x; 1.0019x over previous
.LBB0_323:
	s_and_b32 s22, s1, 63
	s_and_b32 s31, s17, 63
	s_ashr_i32 s26, s17, 6
	s_lshl_b32 s30, s22, 5
	s_lshl_b32 s33, s31, 11
	s_ashr_i32 s27, s26, 31
	s_mul_i32 s23, s26, 0x3000
	s_mul_hi_i32 s22, s26, 0x3000
	s_add_u32 s23, s4, s23
	s_addc_u32 s28, s5, s22
	s_lshl_b32 s36, s31, 6
	s_add_u32 s22, s23, s36
	v_or_b32_e32 v0, s33, v105
	s_addc_u32 s23, s28, 0
	s_lshl_b64 s[28:29], s[26:27], 11
	v_lshlrev_b32_e32 v152, 1, v0
	v_mov_b32_e32 v1, s29
	v_or_b32_e32 v0, s28, v76
	v_lshlrev_b64 v[2:3], 11, v[0:1]
	v_lshl_add_u64 v[2:3], s[10:11], 0, v[2:3]
	s_lshl_b32 s66, s31, 5
	v_lshl_add_u64 v[2:3], v[2:3], 0, s[66:67]
	v_lshl_add_u64 v[16:17], v[80:81], 0, v[152:153]
	v_lshl_add_u64 v[2:3], v[78:79], 1, v[2:3]
	v_lshlrev_b64 v[0:1], 7, v[0:1]
	global_load_dwordx4 v[32:35], v[16:17], off
	global_load_dwordx4 v[36:39], v[16:17], off offset:1024
	v_lshl_add_u64 v[18:19], s[12:13], 0, v[0:1]
	global_load_dwordx4 v[0:3], v[2:3], off
	s_nop 0
	global_load_dwordx4 v[4:7], v[18:19], off
	global_load_dwordx4 v[8:11], v[18:19], off offset:32
	global_load_dwordx4 v[12:15], v[18:19], off offset:16
	global_load_dwordx4 v[40:43], v[16:17], off offset:2048
	global_load_dwordx4 v[44:47], v[16:17], off offset:3072
	v_lshl_or_b32 v16, v77, 2, s36
	global_load_dword v90, v16, s[24:25]
	v_or_b32_e32 v16, s33, v100
	v_lshlrev_b32_e32 v152, 1, v16
	global_load_dwordx4 v[16:19], v[18:19], off offset:48
	v_lshl_add_u32 v22, s31, 7, v101
	v_lshl_add_u64 v[20:21], v[82:83], 0, v[152:153]
	v_ashrrev_i32_e32 v23, 31, v22
	global_load_dwordx4 v[48:51], v[20:21], off
	global_load_dwordx4 v[52:55], v[20:21], off offset:64
	global_load_dwordx4 v[56:59], v[20:21], off offset:128
	global_load_dwordx4 v[60:63], v[20:21], off offset:192
	v_lshl_add_u64 v[22:23], v[22:23], 2, s[20:21]
	v_lshl_add_u64 v[20:21], v[78:79], 2, s[22:23]
	global_load_dwordx2 v[92:93], v[22:23], off
	global_load_dwordx4 v[64:67], v[20:21], off offset:16
	global_load_dwordx4 v[68:71], v[20:21], off
	s_lshl_b64 s[22:23], s[26:27], 22
	s_lshl_b64 s[26:27], s[26:27], 18
	s_or_b32 s22, s22, s30
	v_lshl_add_u64 v[94:95], v[88:89], 0, s[26:27]
	v_lshl_add_u64 v[96:97], v[84:85], 0, s[22:23]
	v_lshl_add_u64 v[98:99], v[86:87], 0, s[22:23]
	v_mov_b32_e32 v112, 0
	s_mov_b64 s[36:37], 0
	v_mov_b32_e32 v113, 0
	s_waitcnt vmcnt(14)
	v_mov_b64_e32 v[74:75], v[2:3]
	v_mov_b64_e32 v[72:73], v[0:1]
	s_waitcnt vmcnt(11)
	v_pk_add_f32 v[6:7], v[6:7], v[14:15]
	v_pk_add_f32 v[4:5], v[4:5], v[12:13]
	v_pk_add_f32 v[6:7], v[6:7], v[10:11]
	v_pk_add_f32 v[4:5], v[4:5], v[8:9]
	s_waitcnt vmcnt(8)
	v_mov_b32_e32 v91, v90
	s_waitcnt vmcnt(7)
	v_pk_add_f32 v[6:7], v[6:7], v[18:19]
	v_pk_add_f32 v[4:5], v[4:5], v[16:17]
	s_nop 0
	v_pk_mov_b32 v[8:9], v[4:5], v[6:7] op_sel:[1,0]
	v_mov_b32_e32 v5, v7
	v_pk_add_f32 v[4:5], v[8:9], v[4:5]
	s_nop 0
	v_add_f32_e32 v4, v4, v5
	v_fmamk_f32 v4, v4, 0x3a800000, v245
	v_rsq_f32_e32 v4, v4
	s_waitcnt vmcnt(0)
	s_branch .LBB0_325
.LBB0_324:
	v_lshlrev_b32_e32 v6, 16, v0
	v_and_b32_e32 v7, 0xffff0000, v0
	v_lshlrev_b32_e32 v0, 16, v1
	v_and_b32_e32 v1, 0xffff0000, v1
	s_waitcnt vmcnt(6)
	v_pk_fma_f32 v[116:117], v[4:5], v[0:1], v[70:71] op_sel_hi:[0,1,1]
	v_lshlrev_b32_e32 v0, 16, v2
	v_and_b32_e32 v1, 0xffff0000, v2
	v_pk_fma_f32 v[118:119], v[4:5], v[0:1], v[64:65] op_sel_hi:[0,1,1]
	v_lshlrev_b32_e32 v0, 16, v3
	v_and_b32_e32 v1, 0xffff0000, v3
	v_pk_fma_f32 v[114:115], v[4:5], v[6:7], v[68:69] op_sel_hi:[0,1,1]
	v_pk_fma_f32 v[120:121], v[4:5], v[0:1], v[66:67] op_sel_hi:[0,1,1]
	v_cvt_pk_bf16_f32 v122, v114, v115
	v_cvt_pk_bf16_f32 v123, v116, v117
	v_cvt_pk_bf16_f32 v124, v118, v119
	v_cvt_pk_bf16_f32 v125, v120, v121
	s_mov_b64 s[22:23], 0x1000
	v_lshl_add_u64 v[94:95], v[94:95], 0, s[22:23]
	v_mfma_f32_32x32x16_bf16 v[16:31], v[122:125], v[32:35], 0
	v_mfma_f32_32x32x16_bf16 v[0:15], v[122:125], v[36:39], 0
	ds_write_b128 v102, v[114:117] offset:27136
	ds_write_b128 v102, v[118:121] offset:27152
	s_nop 8
	ds_write_b128 v106, v[16:19]
	ds_write_b128 v106, v[20:23] offset:32
	ds_write_b128 v106, v[24:27] offset:64
	ds_write_b128 v106, v[28:31] offset:96
	ds_write_b128 v106, v[0:3] offset:4608
	v_mfma_f32_32x32x16_bf16 v[16:31], v[122:125], v[40:43], 0
	ds_write_b128 v106, v[4:7] offset:4640
	ds_write_b128 v106, v[8:11] offset:4672
	ds_write_b128 v106, v[12:15] offset:4704
	s_nop 8
	ds_write_b128 v106, v[16:19] offset:9216
	ds_write_b128 v106, v[20:23] offset:9248
	ds_write_b128 v106, v[24:27] offset:9280
	ds_write_b128 v106, v[28:31] offset:9312
	v_mfma_f32_32x32x16_bf16 v[0:15], v[122:125], v[44:47], 0
	s_nop 11
	ds_write_b128 v106, v[0:3] offset:13824
	ds_write_b128 v106, v[4:7] offset:13856
	ds_write_b128 v106, v[8:11] offset:13888
	ds_write_b128 v106, v[12:15] offset:13920
	ds_read_b128 v[4:7], v107 offset:9216
	ds_read_b128 v[114:117], v107 offset:9232
	ds_read_b128 v[12:15], v107
	ds_read_b128 v[118:121], v107 offset:16
	ds_read_b128 v[122:125], v107 offset:32
	ds_read_b128 v[126:129], v107 offset:48
	ds_read_b128 v[130:133], v107 offset:9248
	ds_read_b128 v[134:137], v107 offset:9264
	ds_read_b128 v[28:31], v107 offset:64
	ds_read_b128 v[20:23], v107 offset:80
	ds_read_b128 v[24:27], v107 offset:9280
	ds_read_b128 v[16:19], v107 offset:9296
	ds_read_b128 v[8:11], v107 offset:96
	ds_read_b128 v[0:3], v107 offset:112
	s_waitcnt lgkmcnt(11)
	v_fma_f32 v12, -v93, v113, v12
	v_fma_f32 v4, v93, v112, v4
	v_fma_f32 v12, v92, v112, v12
	v_fma_f32 v4, v92, v113, v4
	v_fma_f32 v13, -v93, v4, v13
	v_fma_f32 v5, v93, v12, v5
	v_cvt_pk_bf16_f32 v112, v12, v4
	v_fma_f32 v113, v92, v12, v13
	v_fma_f32 v138, v92, v4, v5
	v_fma_f32 v4, -v93, v138, v14
	v_fma_f32 v5, v93, v113, v6
	v_fma_f32 v139, v92, v113, v4
	v_fma_f32 v140, v92, v138, v5
	v_cvt_pk_bf16_f32 v113, v113, v138
	v_add_u32_e32 v138, 0x4800, v108
	v_fma_f32 v141, -v93, v140, v15
	v_fma_f32 v142, v93, v139, v7
	ds_read_b128 v[12:15], v107 offset:9312
	ds_read_b128 v[4:7], v107 offset:9328
	ds_write2_b32 v138, v112, v113 offset1:68
	v_cvt_pk_bf16_f32 v112, v139, v140
	v_fma_f32 v113, v92, v139, v141
	v_fma_f32 v139, v92, v140, v142
	v_cvt_pk_bf16_f32 v140, v113, v139
	ds_write2_b32 v138, v112, v140 offset0:136 offset1:204
	s_waitcnt lgkmcnt(14)
	v_fma_f32 v112, -v93, v139, v118
	v_fma_f32 v114, v93, v113, v114
	v_fma_f32 v112, v92, v113, v112
	v_fma_f32 v113, v92, v139, v114
	v_fma_f32 v118, -v93, v113, v119
	v_fma_f32 v115, v93, v112, v115
	v_cvt_pk_bf16_f32 v114, v112, v113
	v_fma_f32 v112, v92, v112, v118
	v_fma_f32 v113, v92, v113, v115
	v_add_u32_e32 v118, 0x4c00, v108
	v_cvt_pk_bf16_f32 v115, v112, v113
	ds_write2_b32 v118, v114, v115 offset0:16 offset1:84
	v_fma_f32 v115, v93, v112, v116
	v_fma_f32 v114, -v93, v113, v120
	v_fma_f32 v112, v92, v112, v114
	v_fma_f32 v113, v92, v113, v115
	v_fma_f32 v115, -v93, v113, v121
	v_cvt_pk_bf16_f32 v114, v112, v113
	v_fma_f32 v116, v93, v112, v117
	v_fma_f32 v112, v92, v112, v115
	v_fma_f32 v113, v92, v113, v116
	v_cvt_pk_bf16_f32 v115, v112, v113
	ds_write2_b32 v118, v114, v115 offset0:152 offset1:220
	s_waitcnt lgkmcnt(13)
	v_fma_f32 v115, v93, v112, v130
	v_fma_f32 v114, -v93, v113, v122
	v_fma_f32 v112, v92, v112, v114
	v_fma_f32 v113, v92, v113, v115
	v_fma_f32 v115, -v93, v113, v123
	v_fma_f32 v116, v93, v112, v131
	v_cvt_pk_bf16_f32 v114, v112, v113
	v_fma_f32 v112, v92, v112, v115
	v_fma_f32 v113, v92, v113, v116
	v_add_u32_e32 v116, 0x5000, v108
	v_cvt_pk_bf16_f32 v115, v112, v113
	ds_write2_b32 v116, v114, v115 offset0:32 offset1:100
	v_fma_f32 v115, v93, v112, v132
	v_fma_f32 v114, -v93, v113, v124
	v_fma_f32 v112, v92, v112, v114
	v_fma_f32 v113, v92, v113, v115
	v_fma_f32 v115, -v93, v113, v125
	v_cvt_pk_bf16_f32 v114, v112, v113
	v_fma_f32 v117, v93, v112, v133
	v_fma_f32 v112, v92, v112, v115
	v_fma_f32 v113, v92, v113, v117
	v_cvt_pk_bf16_f32 v115, v112, v113
	ds_write2_b32 v116, v114, v115 offset0:168 offset1:236
	s_waitcnt lgkmcnt(14)
	v_fma_f32 v115, v93, v112, v134
	v_fma_f32 v114, -v93, v113, v126
	v_fma_f32 v112, v92, v112, v114
	v_fma_f32 v113, v92, v113, v115
	v_fma_f32 v115, -v93, v113, v127
	v_fma_f32 v116, v93, v112, v135
	v_cvt_pk_bf16_f32 v114, v112, v113
	v_fma_f32 v112, v92, v112, v115
	v_fma_f32 v113, v92, v113, v116
	v_add_u32_e32 v116, 0x5400, v108
	v_cvt_pk_bf16_f32 v115, v112, v113
	ds_write2_b32 v116, v114, v115 offset0:48 offset1:116
	v_fma_f32 v114, -v93, v113, v128
	v_fma_f32 v115, v93, v112, v136
	v_fma_f32 v112, v92, v112, v114
	v_fma_f32 v113, v92, v113, v115
	v_cvt_pk_bf16_f32 v114, v112, v113
	v_fma_f32 v115, -v93, v113, v129
	v_fma_f32 v117, v93, v112, v137
	v_fma_f32 v112, v92, v112, v115
	v_fma_f32 v113, v92, v113, v117
	s_waitcnt lgkmcnt(14)
	v_fma_f32 v28, -v93, v113, v28
	s_waitcnt lgkmcnt(12)
	v_fma_f32 v24, v93, v112, v24
	v_cvt_pk_bf16_f32 v115, v112, v113
	v_fma_f32 v28, v92, v112, v28
	v_fma_f32 v24, v92, v113, v24
	ds_write2_b32 v116, v114, v115 offset0:184 offset1:252
	v_fma_f32 v29, -v93, v24, v29
	v_fma_f32 v25, v93, v28, v25
	v_cvt_pk_bf16_f32 v112, v28, v24
	v_fma_f32 v28, v92, v28, v29
	v_fma_f32 v24, v92, v24, v25
	v_add_u32_e32 v29, 0x5800, v108
	v_cvt_pk_bf16_f32 v25, v28, v24
	ds_write2_b32 v29, v112, v25 offset0:64 offset1:132
	v_fma_f32 v25, -v93, v24, v30
	v_fma_f32 v26, v93, v28, v26
	v_fma_f32 v25, v92, v28, v25
	v_fma_f32 v24, v92, v24, v26
	v_cvt_pk_bf16_f32 v26, v25, v24
	v_fma_f32 v28, -v93, v24, v31
	v_fma_f32 v27, v93, v25, v27
	v_fma_f32 v25, v92, v25, v28
	v_fma_f32 v24, v92, v24, v27
	v_add_u32_e32 v28, 0x5a00, v108
	v_fma_f32 v20, -v93, v24, v20
	s_waitcnt lgkmcnt(13)
	v_fma_f32 v16, v93, v25, v16
	v_cvt_pk_bf16_f32 v27, v25, v24
	v_fma_f32 v20, v92, v25, v20
	v_fma_f32 v16, v92, v24, v16
	ds_write2_b32 v28, v26, v27 offset0:72 offset1:140
	v_fma_f32 v21, -v93, v16, v21
	v_fma_f32 v17, v93, v20, v17
	v_cvt_pk_bf16_f32 v24, v20, v16
	v_fma_f32 v20, v92, v20, v21
	v_fma_f32 v16, v92, v16, v17
	v_add_u32_e32 v21, 0x5c00, v108
	v_cvt_pk_bf16_f32 v17, v20, v16
	ds_write2_b32 v21, v24, v17 offset0:80 offset1:148
	v_fma_f32 v17, -v93, v16, v22
	v_fma_f32 v18, v93, v20, v18
	v_fma_f32 v17, v92, v20, v17
	v_fma_f32 v16, v92, v16, v18
	v_cvt_pk_bf16_f32 v18, v17, v16
	v_fma_f32 v20, -v93, v16, v23
	v_fma_f32 v19, v93, v17, v19
	v_fma_f32 v17, v92, v17, v20
	v_fma_f32 v16, v92, v16, v19
	v_add_u32_e32 v20, 0x5e00, v108
	s_waitcnt lgkmcnt(14)
	v_fma_f32 v8, -v93, v16, v8
	s_waitcnt lgkmcnt(12)
	v_fma_f32 v12, v93, v17, v12
	v_cvt_pk_bf16_f32 v19, v17, v16
	v_fma_f32 v8, v92, v17, v8
	v_fma_f32 v12, v92, v16, v12
	ds_write2_b32 v20, v18, v19 offset0:88 offset1:156
	v_fma_f32 v9, -v93, v12, v9
	v_fma_f32 v13, v93, v8, v13
	v_cvt_pk_bf16_f32 v16, v8, v12
	v_fma_f32 v8, v92, v8, v9
	v_fma_f32 v9, v92, v12, v13
	v_add_u32_e32 v13, 0x6000, v108
	v_cvt_pk_bf16_f32 v12, v8, v9
	ds_write2_b32 v13, v16, v12 offset0:96 offset1:164
	v_fma_f32 v10, -v93, v9, v10
	v_fma_f32 v12, v93, v8, v14
	v_fma_f32 v8, v92, v8, v10
	v_fma_f32 v9, v92, v9, v12
	v_cvt_pk_bf16_f32 v10, v8, v9
	v_fma_f32 v11, -v93, v9, v11
	v_fma_f32 v12, v93, v8, v15
	v_fma_f32 v8, v92, v8, v11
	v_fma_f32 v9, v92, v9, v12
	v_add_u32_e32 v12, 0x6200, v108
	v_fma_f32 v0, -v93, v9, v0
	s_waitcnt lgkmcnt(13)
	v_fma_f32 v4, v93, v8, v4
	v_cvt_pk_bf16_f32 v11, v8, v9
	v_fma_f32 v0, v92, v8, v0
	v_fma_f32 v4, v92, v9, v4
	ds_write2_b32 v12, v10, v11 offset0:104 offset1:172
	v_fma_f32 v1, -v93, v4, v1
	v_fma_f32 v5, v93, v0, v5
	v_cvt_pk_bf16_f32 v8, v0, v4
	v_fma_f32 v0, v92, v0, v1
	v_fma_f32 v1, v92, v4, v5
	v_add_u32_e32 v5, 0x6400, v108
	v_cvt_pk_bf16_f32 v4, v0, v1
	ds_write2_b32 v5, v8, v4 offset0:112 offset1:180
	v_fma_f32 v2, -v93, v1, v2
	v_fma_f32 v4, v93, v0, v6
	v_fma_f32 v0, v92, v0, v2
	v_fma_f32 v1, v92, v1, v4
	v_cvt_pk_bf16_f32 v2, v0, v1
	v_fma_f32 v3, -v93, v1, v3
	v_fma_f32 v4, v93, v0, v7
	v_fma_f32 v112, v92, v0, v3
	v_fma_f32 v113, v92, v1, v4
	v_add_u32_e32 v1, 0x6600, v108
	v_cvt_pk_bf16_f32 v0, v112, v113
	ds_write2_b32 v1, v2, v0 offset0:120 offset1:188
	ds_read_b128 v[0:3], v103 offset:18432
	ds_read_b128 v[4:7], v103 offset:18496
	ds_read_b128 v[8:11], v103 offset:22784
	ds_read_b128 v[12:15], v103 offset:22848
	s_waitcnt lgkmcnt(3)
	v_mfma_f32_16x16x32_bf16 v[0:3], v[0:3], v[48:51], 0
	s_waitcnt lgkmcnt(1)
	v_mfma_f32_16x16x32_bf16 v[8:11], v[8:11], v[48:51], 0
	v_mfma_f32_16x16x32_bf16 v[0:3], v[4:7], v[52:55], v[0:3]
	s_waitcnt lgkmcnt(0)
	v_mfma_f32_16x16x32_bf16 v[4:7], v[12:15], v[52:55], v[8:11]
	s_nop 4
	ds_read_b128 v[8:11], v103 offset:18560
	ds_read_b128 v[12:15], v103 offset:18624
	s_waitcnt lgkmcnt(1)
	v_mfma_f32_16x16x32_bf16 v[0:3], v[8:11], v[56:59], v[0:3]
	ds_read_b128 v[8:11], v103 offset:22912
	ds_read_b128 v[16:19], v103 offset:22976
	s_waitcnt lgkmcnt(1)
	v_mfma_f32_16x16x32_bf16 v[4:7], v[8:11], v[56:59], v[4:7]
	v_add_u32_e32 v10, 0x6800, v109
	ds_read2_b32 v[8:9], v10 offset0:128 offset1:144
	v_mfma_f32_16x16x32_bf16 v[0:3], v[12:15], v[60:63], v[0:3]
	s_waitcnt lgkmcnt(1)
	v_mfma_f32_16x16x32_bf16 v[4:7], v[16:19], v[60:63], v[4:7]
	s_waitcnt lgkmcnt(0)
	s_nop 4
	v_pk_fma_f32 v[0:1], v[90:91], v[8:9], v[0:1]
	s_nop 0
	v_mul_f32_e32 v8, 0x3d372713, v0
	v_mul_f32_e32 v8, v0, v8
	v_fma_f32 v8, v0, v8, v0
	v_mul_f32_e32 v8, 0x3f4c422a, v8
	v_mul_f32_e32 v8, 0xc038aa3b, v8
	v_exp_f32_e32 v11, v8
	v_mul_f32_e32 v8, 0x3d372713, v1
	v_mul_f32_e32 v8, v1, v8
	v_fma_f32 v8, v1, v8, v1
	v_mul_f32_e32 v8, 0x3f4c422a, v8
	v_mul_f32_e32 v8, 0xc038aa3b, v8
	v_exp_f32_e32 v12, v8
	ds_read2_b32 v[8:9], v10 offset0:160 offset1:176
	v_add_f32_e32 v10, 1.0, v11
	v_rcp_f32_e32 v10, v10
	v_add_f32_e32 v11, 1.0, v12
	v_rcp_f32_e32 v11, v11
	s_waitcnt lgkmcnt(0)
	v_pk_fma_f32 v[2:3], v[90:91], v[8:9], v[2:3]
	v_add_u32_e32 v12, 0x6c00, v109
	v_mul_f32_e32 v8, 0x3d372713, v2
	v_mul_f32_e32 v9, 0x3d372713, v3
	v_mul_f32_e32 v8, v2, v8
	v_mul_f32_e32 v9, v3, v9
	v_fma_f32 v8, v2, v8, v2
	v_fma_f32 v9, v3, v9, v3
	v_mul_f32_e32 v8, 0x3f4c422a, v8
	v_mul_f32_e32 v9, 0x3f4c422a, v9
	v_mul_f32_e32 v8, 0xc038aa3b, v8
	v_mul_f32_e32 v9, 0xc038aa3b, v9
	v_exp_f32_e32 v8, v8
	v_exp_f32_e32 v9, v9
	v_pk_mul_f32 v[0:1], v[0:1], v[10:11]
	ds_read2_b32 v[10:11], v12 offset0:128 offset1:144
	v_add_f32_e32 v8, 1.0, v8
	v_add_f32_e32 v9, 1.0, v9
	v_rcp_f32_e32 v8, v8
	v_rcp_f32_e32 v9, v9
	s_nop 0
	v_pk_mul_f32 v[2:3], v[2:3], v[8:9]
	v_cvt_pk_bf16_f32 v8, v0, v1
	s_waitcnt lgkmcnt(0)
	v_pk_fma_f32 v[0:1], v[90:91], v[10:11], v[4:5]
	v_cvt_pk_bf16_f32 v9, v2, v3
	v_mul_f32_e32 v2, 0x3d372713, v0
	v_mul_f32_e32 v2, v0, v2
	v_fma_f32 v2, v0, v2, v0
	v_mul_f32_e32 v2, 0x3f4c422a, v2
	v_mul_f32_e32 v2, 0xc038aa3b, v2
	v_exp_f32_e32 v4, v2
	v_mul_f32_e32 v2, 0x3d372713, v1
	v_mul_f32_e32 v2, v1, v2
	v_fma_f32 v2, v1, v2, v1
	v_mul_f32_e32 v2, 0x3f4c422a, v2
	v_mul_f32_e32 v2, 0xc038aa3b, v2
	v_exp_f32_e32 v5, v2
	ds_read2_b32 v[2:3], v12 offset0:160 offset1:176
	v_add_f32_e32 v4, 1.0, v4
	v_rcp_f32_e32 v4, v4
	v_add_f32_e32 v5, 1.0, v5
	v_rcp_f32_e32 v5, v5
	s_waitcnt lgkmcnt(0)
	v_pk_fma_f32 v[2:3], v[90:91], v[2:3], v[6:7]
	ds_write_b16 v110, v8 offset:29184
	v_mul_f32_e32 v6, 0x3d372713, v2
	v_mul_f32_e32 v7, 0x3d372713, v3
	v_mul_f32_e32 v6, v2, v6
	v_mul_f32_e32 v7, v3, v7
	v_fma_f32 v6, v2, v6, v2
	v_fma_f32 v7, v3, v7, v3
	v_mul_f32_e32 v6, 0x3f4c422a, v6
	v_mul_f32_e32 v7, 0x3f4c422a, v7
	v_mul_f32_e32 v6, 0xc038aa3b, v6
	v_mul_f32_e32 v7, 0xc038aa3b, v7
	v_exp_f32_e32 v6, v6
	v_exp_f32_e32 v7, v7
	v_pk_mul_f32 v[0:1], v[0:1], v[4:5]
	ds_write_b16_d16_hi v110, v8 offset:29216
	v_add_f32_e32 v6, 1.0, v6
	v_add_f32_e32 v7, 1.0, v7
	v_rcp_f32_e32 v6, v6
	v_rcp_f32_e32 v7, v7
	v_cvt_pk_bf16_f32 v0, v0, v1
	ds_write_b16 v110, v9 offset:29248
	ds_write_b16_d16_hi v110, v9 offset:29280
	v_lshl_add_u64 v[4:5], v[96:97], 0, s[36:37]
	v_pk_mul_f32 v[2:3], v[2:3], v[6:7]
	s_add_u32 s36, s36, 0x10000
	v_cvt_pk_bf16_f32 v1, v2, v3
	ds_write_b16 v110, v0 offset:29696
	ds_write_b16_d16_hi v110, v0 offset:29728
	ds_write_b16 v110, v1 offset:29760
	ds_write_b16_d16_hi v110, v1 offset:29792
	ds_read_b128 v[0:3], v104 offset:29184
	s_addc_u32 s37, s37, 0
	s_cmp_eq_u32 s36, 0x400000
	s_waitcnt lgkmcnt(0)
	global_store_dwordx4 v[4:5], v[0:3], off
	s_nop 1
	s_waitcnt vmcnt(1)
	v_pk_add_f32 v[228:229], v[228:229], v[232:233]
	v_pk_add_f32 v[226:227], v[226:227], v[230:231]
	v_pk_add_f32 v[228:229], v[228:229], v[238:239]
	v_pk_add_f32 v[226:227], v[226:227], v[236:237]
	v_pk_add_f32 v[228:229], v[228:229], v[242:243]
	v_pk_add_f32 v[226:227], v[226:227], v[240:241]
	s_nop 0
	v_pk_mov_b32 v[230:231], v[226:227], v[228:229] op_sel:[1,0]
	v_mov_b32_e32 v227, v229
	v_pk_add_f32 v[226:227], v[230:231], v[226:227]
	s_nop 0
	v_add_f32_e32 v230, v226, v227
	v_fmamk_f32 v230, v230, 0x3a800000, v245
	v_rsq_f32_e32 v111, v230
	v_mov_b64_e32 v[0:1], v[72:73]
	v_mov_b64_e32 v[2:3], v[74:75]
	v_mov_b32_e32 v4, v111
	s_cbranch_scc1 .LBB0_322
.LBB0_325:
	s_cmp_eq_u32 s36, 0x3f0000
	v_mov_b32_e32 v111, v4
	s_cbranch_scc1 .LBB0_324
	global_load_dwordx4 v[226:229], v[94:95], off offset:-32
	global_load_dwordx4 v[230:233], v[94:95], off offset:-16
	global_load_dwordx4 v[236:239], v[94:95], off
	global_load_dwordx4 v[240:243], v[94:95], off offset:16
	v_lshl_add_u64 v[22:23], v[98:99], 0, s[36:37]
	global_load_dwordx4 v[72:75], v[22:23], off
	s_branch .LBB0_324
